# speedup vs baseline: 1.0057x; 1.0057x over previous
; #define PG8_STAGE(bufoff, gbase, voff) do { _Pragma("unroll") for (int _i = 0; _i < 2; ++_i) \
;         __builtin_amdgcn_global_load_lds((const unsigned*)((const char*)(gbase) + (voff)[_i]), (LAS unsigned*)(lds + (bufoff) + ldsw + _i * 8192), 16, 0, 0); } while (0)
; #define PG8_LDA(dst, b, h) do { _Pragma("unroll") for (int m = 0; m < 4; ++m) _Pragma("unroll") for (int k = 0; k < 2; ++k) dst[m][k] = *(const LAS bf16x8*)(lds + PG8_SA(b, h) + aoff + m * 2048 + k * 1024); } while (0)
; #define PG8_LDB(dst, b, h) do { _Pragma("unroll") for (int n = 0; n < 2; ++n) _Pragma("unroll") for (int k = 0; k < 2; ++k) dst[n][k] = *(const LAS bf16x8*)(lds + PG8_SB(b, h) + boff + n * 2048 + k * 1024); } while (0)
; #define PG8_MMA(ai, bj, At, Bt) do { __builtin_amdgcn_s_setprio(1); _Pragma("unroll") for (int m = 0; m < 4; ++m) _Pragma("unroll") for (int n = 0; n < 2; ++n) _Pragma("unroll") for (int k = 0; k < 2; ++k) \
;         acc[ai][bj][m][n] = __builtin_amdgcn_mfma_f32_16x16x32_bf16(Bt[n][k], At[m][k], acc[ai][bj][m][n], 0, 0, 0); __builtin_amdgcn_s_setprio(0); } while (0)
; #define PG8_WAIT_L(n) asm volatile("s_waitcnt lgkmcnt(" #n ")" ::: "memory")
; #define PG8_BAR __builtin_amdgcn_s_barrier()
; #define PG8_SCHED __builtin_amdgcn_sched_barrier(0)
; __device__ __forceinline__ void gemm_phase(LAS unsigned char* lds, const GemmD& g) {
;     ...
;             PG8_LDB(B0, 0, 0); PG8_SCHED; PG8_LDA(At, 0, 0); PG8_STAGE(PG8_SA(1, 1), a1 + hstep, voffA);
;             PG8_WAIT_L(8); PG8_BAR; PG8_WAIT_L(0); PG8_MMA(0, 0, At, B0); PG8_BAR; PG8_SCHED;
;             PG8_LDB(B1, 0, 1); PG8_STAGE(PG8_SB(0, 0), b2, voffB);
;             PG8_BAR; PG8_WAIT_L(0); PG8_MMA(0, 1, At, B1); PG8_BAR;
;             PG8_LDA(At, 0, 1); PG8_STAGE(PG8_SA(0, 0), a2, voffA);
;             PG8_BAR; PG8_WAIT_L(0); PG8_MMA(1, 0, At, B0); PG8_BAR; PG8_SCHED;
.LBB0_145:
	s_add_i32 s6, 0, 0x10000
	v_add_u32_e32 v148, s6, v229
	ds_read_b128 v[136:139], v148
	ds_read_b128 v[140:143], v148 offset:1024
	ds_read_b128 v[144:147], v148 offset:2048
	ds_read_b128 v[148:151], v148 offset:3072
	v_lshl_add_u64 v[152:153], v[130:131], 0, s[44:45]
	v_cmp_eq_u32_e32 vcc, s4, v135
	s_add_i32 s5, s4, 2
	s_nop 0
	v_cndmask_b32_e32 v165, v153, v181, vcc
	v_cndmask_b32_e32 v164, v152, v180, vcc
	v_cndmask_b32_e32 v243, v133, v183, vcc
	v_cndmask_b32_e32 v242, v132, v182, vcc
	v_lshl_add_u64 v[204:205], v[130:131], 0, v[174:175]
	s_add_i32 m0, s2, 0xc000
	ds_read_b128 v[152:155], v233
	ds_read_b128 v[156:159], v233 offset:1024
	ds_read_b128 v[160:163], v233 offset:2048
	ds_read_b128 v[184:187], v233 offset:3072
	ds_read_b128 v[188:191], v233 offset:4096
	ds_read_b128 v[192:195], v233 offset:5120
	ds_read_b128 v[196:199], v233 offset:6144
	ds_read_b128 v[200:203], v233 offset:7168
	global_load_lds_dwordx4 v[204:205], off
	v_lshl_add_u64 v[204:205], v[130:131], 0, v[176:177]
	s_add_i32 m0, s2, 0xe000
	s_nop 0
	global_load_lds_dwordx4 v[204:205], off
	s_waitcnt lgkmcnt(8)
	s_barrier
	s_waitcnt lgkmcnt(0)
	v_mfma_f32_16x16x32_bf16 v[126:129], v[136:139], v[152:155], v[126:129]
	v_mfma_f32_16x16x32_bf16 v[122:125], v[144:147], v[152:155], v[122:125]
	v_mfma_f32_16x16x32_bf16 v[110:113], v[136:139], v[160:163], v[110:113]
	v_mfma_f32_16x16x32_bf16 v[106:109], v[144:147], v[160:163], v[106:109]
	v_mfma_f32_16x16x32_bf16 v[94:97], v[136:139], v[188:191], v[94:97]
	v_mfma_f32_16x16x32_bf16 v[90:93], v[144:147], v[188:191], v[90:93]
	v_mfma_f32_16x16x32_bf16 v[78:81], v[136:139], v[196:199], v[78:81]
	v_mfma_f32_16x16x32_bf16 v[74:77], v[144:147], v[196:199], v[74:77]
	v_mfma_f32_16x16x32_bf16 v[126:129], v[140:143], v[156:159], v[126:129]
	v_mfma_f32_16x16x32_bf16 v[122:125], v[148:151], v[156:159], v[122:125]
	v_mfma_f32_16x16x32_bf16 v[110:113], v[140:143], v[184:187], v[110:113]
	v_mfma_f32_16x16x32_bf16 v[106:109], v[148:151], v[184:187], v[106:109]
	v_mfma_f32_16x16x32_bf16 v[94:97], v[140:143], v[192:195], v[94:97]
	v_mfma_f32_16x16x32_bf16 v[90:93], v[148:151], v[192:195], v[90:93]
	v_mfma_f32_16x16x32_bf16 v[78:81], v[140:143], v[200:203], v[78:81]
	v_mfma_f32_16x16x32_bf16 v[74:77], v[148:151], v[200:203], v[74:77]
	s_barrier
	s_add_i32 s4, 0, 0x14000
	s_add_i32 s6, s6, s87
	v_add_u32_e32 v238, s4, v229
	v_lshl_add_u64 v[244:245], v[242:243], 0, v[172:173]
	s_mov_b32 m0, s6
	ds_read_b128 v[204:207], v238
	ds_read_b128 v[208:211], v238 offset:1024
	ds_read_b128 v[234:237], v238 offset:2048
	ds_read_b128 v[238:241], v238 offset:3072
	global_load_lds_dwordx4 v[244:245], off
	v_lshl_add_u64 v[246:247], v[242:243], 0, v[168:169]
	s_add_i32 m0, s6, 0x2000
	s_nop 0
	global_load_lds_dwordx4 v[246:247], off
	s_barrier
	s_waitcnt lgkmcnt(0)
	v_mfma_f32_16x16x32_bf16 v[118:121], v[204:207], v[152:155], v[118:121]
	v_mfma_f32_16x16x32_bf16 v[114:117], v[234:237], v[152:155], v[114:117]
	v_mfma_f32_16x16x32_bf16 v[102:105], v[204:207], v[160:163], v[102:105]
	v_mfma_f32_16x16x32_bf16 v[98:101], v[234:237], v[160:163], v[98:101]
	v_mfma_f32_16x16x32_bf16 v[86:89], v[204:207], v[188:191], v[86:89]
	v_mfma_f32_16x16x32_bf16 v[82:85], v[234:237], v[188:191], v[82:85]
	v_mfma_f32_16x16x32_bf16 v[70:73], v[204:207], v[196:199], v[70:73]
	v_mfma_f32_16x16x32_bf16 v[66:69], v[234:237], v[196:199], v[66:69]
	v_mfma_f32_16x16x32_bf16 v[118:121], v[208:211], v[156:159], v[118:121]
	v_mfma_f32_16x16x32_bf16 v[114:117], v[238:241], v[156:159], v[114:117]
	v_mfma_f32_16x16x32_bf16 v[102:105], v[208:211], v[184:187], v[102:105]
	v_mfma_f32_16x16x32_bf16 v[98:101], v[238:241], v[184:187], v[98:101]
	v_mfma_f32_16x16x32_bf16 v[86:89], v[208:211], v[192:195], v[86:89]
	v_mfma_f32_16x16x32_bf16 v[82:85], v[238:241], v[192:195], v[82:85]
	v_mfma_f32_16x16x32_bf16 v[70:73], v[208:211], v[200:203], v[70:73]
	v_mfma_f32_16x16x32_bf16 v[66:69], v[238:241], v[200:203], v[66:69]
	s_barrier
	s_mov_b32 m0, s2
	v_lshl_add_u64 v[248:249], v[164:165], 0, v[170:171]
	ds_read_b128 v[152:155], v233 offset:16384
	ds_read_b128 v[156:159], v233 offset:17408
	ds_read_b128 v[160:163], v233 offset:18432
	ds_read_b128 v[184:187], v233 offset:19456
	ds_read_b128 v[188:191], v233 offset:20480
	ds_read_b128 v[192:195], v233 offset:21504
	ds_read_b128 v[196:199], v233 offset:22528
	ds_read_b128 v[200:203], v233 offset:23552
	global_load_lds_dwordx4 v[248:249], off
	v_lshl_add_u64 v[250:251], v[164:165], 0, v[166:167]
	s_mov_b32 m0, s3
	s_nop 0
	global_load_lds_dwordx4 v[250:251], off
	s_barrier
	s_waitcnt lgkmcnt(0)
	v_mfma_f32_16x16x32_bf16 v[62:65], v[136:139], v[152:155], v[62:65]
	v_mfma_f32_16x16x32_bf16 v[58:61], v[144:147], v[152:155], v[58:61]
	v_mfma_f32_16x16x32_bf16 v[46:49], v[136:139], v[160:163], v[46:49]
	v_mfma_f32_16x16x32_bf16 v[42:45], v[144:147], v[160:163], v[42:45]
	v_mfma_f32_16x16x32_bf16 v[30:33], v[136:139], v[188:191], v[30:33]
	v_mfma_f32_16x16x32_bf16 v[26:29], v[144:147], v[188:191], v[26:29]
	v_mfma_f32_16x16x32_bf16 v[14:17], v[136:139], v[196:199], v[14:17]
	v_mfma_f32_16x16x32_bf16 v[10:13], v[144:147], v[196:199], v[10:13]
	v_mfma_f32_16x16x32_bf16 v[62:65], v[140:143], v[156:159], v[62:65]
	v_mfma_f32_16x16x32_bf16 v[58:61], v[148:151], v[156:159], v[58:61]
	v_mfma_f32_16x16x32_bf16 v[46:49], v[140:143], v[184:187], v[46:49]
	v_mfma_f32_16x16x32_bf16 v[42:45], v[148:151], v[184:187], v[42:45]
	v_mfma_f32_16x16x32_bf16 v[30:33], v[140:143], v[192:195], v[30:33]
	v_mfma_f32_16x16x32_bf16 v[26:29], v[148:151], v[192:195], v[26:29]
	v_mfma_f32_16x16x32_bf16 v[14:17], v[140:143], v[200:203], v[14:17]
	v_mfma_f32_16x16x32_bf16 v[10:13], v[148:151], v[200:203], v[10:13]
	s_barrier
; #define PG8_STAGE(bufoff, gbase, voff) do { _Pragma("unroll") for (int _i = 0; _i < 2; ++_i) \
;         __builtin_amdgcn_global_load_lds((const unsigned*)((const char*)(gbase) + (voff)[_i]), (LAS unsigned*)(lds + (bufoff) + ldsw + _i * 8192), 16, 0, 0); } while (0)
; #define PG8_LDA(dst, b, h) do { _Pragma("unroll") for (int m = 0; m < 4; ++m) _Pragma("unroll") for (int k = 0; k < 2; ++k) dst[m][k] = *(const LAS bf16x8*)(lds + PG8_SA(b, h) + aoff + m * 2048 + k * 1024); } while (0)
; #define PG8_LDB(dst, b, h) do { _Pragma("unroll") for (int n = 0; n < 2; ++n) _Pragma("unroll") for (int k = 0; k < 2; ++k) dst[n][k] = *(const LAS bf16x8*)(lds + PG8_SB(b, h) + boff + n * 2048 + k * 1024); } while (0)
; #define PG8_MMA(ai, bj, At, Bt) do { __builtin_amdgcn_s_setprio(1); _Pragma("unroll") for (int m = 0; m < 4; ++m) _Pragma("unroll") for (int n = 0; n < 2; ++n) _Pragma("unroll") for (int k = 0; k < 2; ++k) \
;         acc[ai][bj][m][n] = __builtin_amdgcn_mfma_f32_16x16x32_bf16(Bt[n][k], At[m][k], acc[ai][bj][m][n], 0, 0, 0); __builtin_amdgcn_s_setprio(0); } while (0)
; #define PG8_WAIT_V(n) asm volatile("s_waitcnt vmcnt(" #n ")" ::: "memory")
; #define PG8_WAIT_L(n) asm volatile("s_waitcnt lgkmcnt(" #n ")" ::: "memory")
; #define PG8_BAR __builtin_amdgcn_s_barrier()
; #define PG8_SCHED __builtin_amdgcn_sched_barrier(0)
; __device__ __forceinline__ void gemm_phase(LAS unsigned char* lds, const GemmD& g) {
;     ...
;             PG8_STAGE(PG8_SB(0, 1), b2 + hstep, voffB);
;             PG8_WAIT_V(6); PG8_BAR; PG8_MMA(1, 1, At, B1); PG8_BAR;
;             PG8_LDB(B0, 1, 0); PG8_SCHED; PG8_LDA(At, 1, 0); PG8_STAGE(PG8_SA(0, 1), a2 + hstep, voffA);
;             PG8_WAIT_L(8); PG8_BAR; PG8_WAIT_L(0); PG8_MMA(0, 0, At, B0); PG8_BAR; PG8_SCHED;
	v_lshl_add_u64 v[136:137], v[242:243], 0, s[72:73]
	s_add_i32 s4, s4, s87
	v_lshl_add_u64 v[242:243], v[136:137], 0, v[172:173]
	s_mov_b32 m0, s4
	v_lshl_add_u64 v[252:253], v[136:137], 0, v[168:169]
	global_load_lds_dwordx4 v[242:243], off
	s_add_i32 m0, s4, 0x2000
	s_nop 0
	global_load_lds_dwordx4 v[252:253], off
	s_waitcnt vmcnt(6)
	s_barrier
	v_mfma_f32_16x16x32_bf16 v[54:57], v[204:207], v[152:155], v[54:57]
	v_mfma_f32_16x16x32_bf16 v[50:53], v[234:237], v[152:155], v[50:53]
	v_mfma_f32_16x16x32_bf16 v[38:41], v[204:207], v[160:163], v[38:41]
	v_mfma_f32_16x16x32_bf16 v[34:37], v[234:237], v[160:163], v[34:37]
	v_mfma_f32_16x16x32_bf16 v[22:25], v[204:207], v[188:191], v[22:25]
	v_mfma_f32_16x16x32_bf16 v[18:21], v[234:237], v[188:191], v[18:21]
	v_mfma_f32_16x16x32_bf16 v[6:9], v[204:207], v[196:199], v[6:9]
	v_mfma_f32_16x16x32_bf16 v[2:5], v[234:237], v[196:199], v[2:5]
	v_mfma_f32_16x16x32_bf16 v[54:57], v[208:211], v[156:159], v[54:57]
	v_mfma_f32_16x16x32_bf16 v[50:53], v[238:241], v[156:159], v[50:53]
	v_mfma_f32_16x16x32_bf16 v[38:41], v[208:211], v[184:187], v[38:41]
	v_mfma_f32_16x16x32_bf16 v[34:37], v[238:241], v[184:187], v[34:37]
	v_mfma_f32_16x16x32_bf16 v[22:25], v[208:211], v[192:195], v[22:25]
	v_mfma_f32_16x16x32_bf16 v[18:21], v[238:241], v[192:195], v[18:21]
	v_mfma_f32_16x16x32_bf16 v[6:9], v[208:211], v[200:203], v[6:9]
	v_mfma_f32_16x16x32_bf16 v[2:5], v[238:241], v[200:203], v[2:5]
	s_barrier
	s_add_i32 s4, 0, 0x18000
	v_add_u32_e32 v148, s4, v229
	ds_read_b128 v[136:139], v148
	ds_read_b128 v[140:143], v148 offset:1024
	ds_read_b128 v[144:147], v148 offset:2048
	ds_read_b128 v[148:151], v148 offset:3072
	v_lshl_add_u64 v[164:165], v[164:165], 0, s[72:73]
	s_mov_b32 m0, s64
	v_lshl_add_u64 v[204:205], v[164:165], 0, v[170:171]
	ds_read_b128 v[152:155], v233 offset:32768
	ds_read_b128 v[156:159], v233 offset:33792
	ds_read_b128 v[160:163], v233 offset:34816
	ds_read_b128 v[184:187], v233 offset:35840
	ds_read_b128 v[188:191], v233 offset:36864
	ds_read_b128 v[192:195], v233 offset:37888
	ds_read_b128 v[196:199], v233 offset:38912
	ds_read_b128 v[200:203], v233 offset:39936
	global_load_lds_dwordx4 v[204:205], off
	v_lshl_add_u64 v[164:165], v[164:165], 0, v[166:167]
	s_mov_b32 m0, s65
	s_nop 0
	global_load_lds_dwordx4 v[164:165], off
	s_waitcnt lgkmcnt(8)
	s_barrier
	s_waitcnt lgkmcnt(0)
	v_mfma_f32_16x16x32_bf16 v[126:129], v[136:139], v[152:155], v[126:129]
	v_mfma_f32_16x16x32_bf16 v[122:125], v[144:147], v[152:155], v[122:125]
	v_mfma_f32_16x16x32_bf16 v[110:113], v[136:139], v[160:163], v[110:113]
	v_mfma_f32_16x16x32_bf16 v[106:109], v[144:147], v[160:163], v[106:109]
	v_mfma_f32_16x16x32_bf16 v[94:97], v[136:139], v[188:191], v[94:97]
	v_mfma_f32_16x16x32_bf16 v[90:93], v[144:147], v[188:191], v[90:93]
	v_mfma_f32_16x16x32_bf16 v[78:81], v[136:139], v[196:199], v[78:81]
	v_mfma_f32_16x16x32_bf16 v[74:77], v[144:147], v[196:199], v[74:77]
	v_mfma_f32_16x16x32_bf16 v[126:129], v[140:143], v[156:159], v[126:129]
	v_mfma_f32_16x16x32_bf16 v[122:125], v[148:151], v[156:159], v[122:125]
	v_mfma_f32_16x16x32_bf16 v[110:113], v[140:143], v[184:187], v[110:113]
	v_mfma_f32_16x16x32_bf16 v[106:109], v[148:151], v[184:187], v[106:109]
	v_mfma_f32_16x16x32_bf16 v[94:97], v[140:143], v[192:195], v[94:97]
	v_mfma_f32_16x16x32_bf16 v[90:93], v[148:151], v[192:195], v[90:93]
	v_mfma_f32_16x16x32_bf16 v[78:81], v[140:143], v[200:203], v[78:81]
	v_mfma_f32_16x16x32_bf16 v[74:77], v[148:151], v[200:203], v[74:77]
	s_barrier
	s_add_i32 s6, 0, 0x1c000
	v_add_u32_e32 v164, s6, v229
	s_add_i32 s4, s4, s87
	ds_read_b128 v[204:207], v164
	ds_read_b128 v[208:211], v164 offset:1024
	ds_read_b128 v[234:237], v164 offset:2048
	ds_read_b128 v[238:241], v164 offset:3072
	v_lshl_add_u64 v[164:165], v[244:245], 0, s[44:45]
	s_mov_b32 m0, s4
	s_nop 0
	global_load_lds_dwordx4 v[164:165], off
	v_lshl_add_u64 v[164:165], v[246:247], 0, s[44:45]
	s_add_i32 m0, s4, 0x2000
	s_nop 0
	global_load_lds_dwordx4 v[164:165], off
	s_barrier
; #define PG8_STAGE(bufoff, gbase, voff) do { _Pragma("unroll") for (int _i = 0; _i < 2; ++_i) \
;         __builtin_amdgcn_global_load_lds((const unsigned*)((const char*)(gbase) + (voff)[_i]), (LAS unsigned*)(lds + (bufoff) + ldsw + _i * 8192), 16, 0, 0); } while (0)
; #define PG8_LDA(dst, b, h) do { _Pragma("unroll") for (int m = 0; m < 4; ++m) _Pragma("unroll") for (int k = 0; k < 2; ++k) dst[m][k] = *(const LAS bf16x8*)(lds + PG8_SA(b, h) + aoff + m * 2048 + k * 1024); } while (0)
; #define PG8_LDB(dst, b, h) do { _Pragma("unroll") for (int n = 0; n < 2; ++n) _Pragma("unroll") for (int k = 0; k < 2; ++k) dst[n][k] = *(const LAS bf16x8*)(lds + PG8_SB(b, h) + boff + n * 2048 + k * 1024); } while (0)
; #define PG8_MMA(ai, bj, At, Bt) do { __builtin_amdgcn_s_setprio(1); _Pragma("unroll") for (int m = 0; m < 4; ++m) _Pragma("unroll") for (int n = 0; n < 2; ++n) _Pragma("unroll") for (int k = 0; k < 2; ++k) \
;         acc[ai][bj][m][n] = __builtin_amdgcn_mfma_f32_16x16x32_bf16(Bt[n][k], At[m][k], acc[ai][bj][m][n], 0, 0, 0); __builtin_amdgcn_s_setprio(0); } while (0)
; #define PG8_WAIT_V(n) asm volatile("s_waitcnt vmcnt(" #n ")" ::: "memory")
; #define PG8_WAIT_L(n) asm volatile("s_waitcnt lgkmcnt(" #n ")" ::: "memory")
; #define PG8_BAR __builtin_amdgcn_s_barrier()
; #define PG8_SCHED __builtin_amdgcn_sched_barrier(0)
; __device__ __forceinline__ void gemm_phase(LAS unsigned char* lds, const GemmD& g) {
;     ...
;             PG8_LDB(B1, 1, 1); PG8_STAGE(PG8_SB(1, 0), b3, voffB);
;             PG8_BAR; PG8_WAIT_L(0); PG8_MMA(0, 1, At, B1); PG8_BAR;
;             PG8_LDA(At, 1, 1); PG8_STAGE(PG8_SA(1, 0), a3, voffA);
;             PG8_BAR; PG8_WAIT_L(0); PG8_MMA(1, 0, At, B0); PG8_BAR; PG8_SCHED;
;             PG8_STAGE(PG8_SB(1, 1), b3 + hstep, voffB);
;             PG8_WAIT_V(6); PG8_BAR; PG8_MMA(1, 1, At, B1); PG8_BAR;
;         }
	s_waitcnt lgkmcnt(0)
	v_mfma_f32_16x16x32_bf16 v[118:121], v[204:207], v[152:155], v[118:121]
	v_mfma_f32_16x16x32_bf16 v[114:117], v[234:237], v[152:155], v[114:117]
	v_mfma_f32_16x16x32_bf16 v[102:105], v[204:207], v[160:163], v[102:105]
	v_mfma_f32_16x16x32_bf16 v[98:101], v[234:237], v[160:163], v[98:101]
	v_mfma_f32_16x16x32_bf16 v[86:89], v[204:207], v[188:191], v[86:89]
	v_mfma_f32_16x16x32_bf16 v[82:85], v[234:237], v[188:191], v[82:85]
	v_mfma_f32_16x16x32_bf16 v[70:73], v[204:207], v[196:199], v[70:73]
	v_mfma_f32_16x16x32_bf16 v[66:69], v[234:237], v[196:199], v[66:69]
	v_mfma_f32_16x16x32_bf16 v[118:121], v[208:211], v[156:159], v[118:121]
	v_mfma_f32_16x16x32_bf16 v[114:117], v[238:241], v[156:159], v[114:117]
	v_mfma_f32_16x16x32_bf16 v[102:105], v[208:211], v[184:187], v[102:105]
	v_mfma_f32_16x16x32_bf16 v[98:101], v[238:241], v[184:187], v[98:101]
	v_mfma_f32_16x16x32_bf16 v[86:89], v[208:211], v[192:195], v[86:89]
	v_mfma_f32_16x16x32_bf16 v[82:85], v[238:241], v[192:195], v[82:85]
	v_mfma_f32_16x16x32_bf16 v[70:73], v[208:211], v[200:203], v[70:73]
	v_mfma_f32_16x16x32_bf16 v[66:69], v[238:241], v[200:203], v[66:69]
	s_barrier
	s_mov_b32 m0, s28
	v_lshl_add_u64 v[164:165], v[248:249], 0, s[44:45]
	ds_read_b128 v[152:155], v233 offset:49152
	ds_read_b128 v[156:159], v233 offset:50176
	ds_read_b128 v[160:163], v233 offset:51200
	ds_read_b128 v[184:187], v233 offset:52224
	ds_read_b128 v[188:191], v233 offset:53248
	ds_read_b128 v[192:195], v233 offset:54272
	ds_read_b128 v[196:199], v233 offset:55296
	ds_read_b128 v[200:203], v233 offset:56320
	global_load_lds_dwordx4 v[164:165], off
	v_lshl_add_u64 v[164:165], v[250:251], 0, s[44:45]
	s_mov_b32 m0, s29
	s_nop 0
	global_load_lds_dwordx4 v[164:165], off
	s_barrier
	s_waitcnt lgkmcnt(0)
	v_mfma_f32_16x16x32_bf16 v[62:65], v[136:139], v[152:155], v[62:65]
	v_mfma_f32_16x16x32_bf16 v[58:61], v[144:147], v[152:155], v[58:61]
	v_mfma_f32_16x16x32_bf16 v[46:49], v[136:139], v[160:163], v[46:49]
	v_mfma_f32_16x16x32_bf16 v[42:45], v[144:147], v[160:163], v[42:45]
	v_mfma_f32_16x16x32_bf16 v[30:33], v[136:139], v[188:191], v[30:33]
	v_mfma_f32_16x16x32_bf16 v[26:29], v[144:147], v[188:191], v[26:29]
	v_mfma_f32_16x16x32_bf16 v[14:17], v[136:139], v[196:199], v[14:17]
	v_mfma_f32_16x16x32_bf16 v[10:13], v[144:147], v[196:199], v[10:13]
	v_mfma_f32_16x16x32_bf16 v[62:65], v[140:143], v[156:159], v[62:65]
	v_mfma_f32_16x16x32_bf16 v[58:61], v[148:151], v[156:159], v[58:61]
	v_mfma_f32_16x16x32_bf16 v[46:49], v[140:143], v[184:187], v[46:49]
	v_mfma_f32_16x16x32_bf16 v[42:45], v[148:151], v[184:187], v[42:45]
	v_mfma_f32_16x16x32_bf16 v[30:33], v[140:143], v[192:195], v[30:33]
	v_mfma_f32_16x16x32_bf16 v[26:29], v[148:151], v[192:195], v[26:29]
	v_mfma_f32_16x16x32_bf16 v[14:17], v[140:143], v[200:203], v[14:17]
	v_mfma_f32_16x16x32_bf16 v[10:13], v[148:151], v[200:203], v[10:13]
	s_barrier
	s_add_i32 s4, s6, s87
	v_lshl_add_u64 v[136:137], v[242:243], 0, s[44:45]
	s_mov_b32 m0, s4
	s_nop 0
	global_load_lds_dwordx4 v[136:137], off
	v_lshl_add_u64 v[136:137], v[252:253], 0, s[44:45]
	s_add_i32 m0, s4, 0x2000
	s_nop 0
	global_load_lds_dwordx4 v[136:137], off
	v_cmp_ge_u32_e32 vcc, s5, v134
	v_lshl_add_u64 v[130:131], v[130:131], 0, s[46:47]
	v_lshl_add_u64 v[132:133], v[132:133], 0, s[46:47]
	s_mov_b32 s4, s5
	s_waitcnt vmcnt(6)
	s_barrier
	v_mfma_f32_16x16x32_bf16 v[54:57], v[204:207], v[152:155], v[54:57]
	v_mfma_f32_16x16x32_bf16 v[50:53], v[234:237], v[152:155], v[50:53]
	v_mfma_f32_16x16x32_bf16 v[38:41], v[204:207], v[160:163], v[38:41]
	v_mfma_f32_16x16x32_bf16 v[34:37], v[234:237], v[160:163], v[34:37]
	v_mfma_f32_16x16x32_bf16 v[22:25], v[204:207], v[188:191], v[22:25]
	v_mfma_f32_16x16x32_bf16 v[18:21], v[234:237], v[188:191], v[18:21]
	v_mfma_f32_16x16x32_bf16 v[6:9], v[204:207], v[196:199], v[6:9]
	v_mfma_f32_16x16x32_bf16 v[2:5], v[234:237], v[196:199], v[2:5]
	v_mfma_f32_16x16x32_bf16 v[54:57], v[208:211], v[156:159], v[54:57]
	v_mfma_f32_16x16x32_bf16 v[50:53], v[238:241], v[156:159], v[50:53]
	v_mfma_f32_16x16x32_bf16 v[38:41], v[208:211], v[184:187], v[38:41]
	v_mfma_f32_16x16x32_bf16 v[34:37], v[238:241], v[184:187], v[34:37]
	v_mfma_f32_16x16x32_bf16 v[22:25], v[208:211], v[192:195], v[22:25]
	v_mfma_f32_16x16x32_bf16 v[18:21], v[238:241], v[192:195], v[18:21]
	v_mfma_f32_16x16x32_bf16 v[6:9], v[208:211], v[200:203], v[6:9]
	v_mfma_f32_16x16x32_bf16 v[2:5], v[238:241], v[200:203], v[2:5]
	s_barrier
	s_cbranch_vccz .LBB0_145
	v_lshl_add_u32 v184, s56, 8, v228
	s_cmp_lt_i32 s66, 0
	s_mov_b64 s[4:5], -1
	s_cbranch_scc0 .LBB0_704
